# hoist tool now deletes moved reads without nop padding, merges lgkmcnt waits, removes dead address code, and re-checks hazard distances
# baseline (speedup 1.0000x reference)
.LBB0_405:
	s_or_b64 exec, exec, s[76:77]
	s_mul_i32 s29, s78, 0x7c00
	ds_read_u16 v129, v43 offset:60576
	ds_read_u16 v130, v40 offset:60576
	ds_read_u16 v131, v38 offset:60576
	ds_read_u16 v132, v39 offset:60576
	ds_read_u16 v133, v36 offset:60576
	ds_read_u16 v134, v37 offset:60576
	ds_read_u16 v135, v36 offset:60032
	ds_read_u16 v136, v36 offset:60304
	v_mov_b32_e32 v137, s31
	ds_read_b32 v138, v137 offset:252
	v_add_u32_e32 v139, s29, v92
	ds_read_b128 v[140:143], v139
	ds_read_u16 v144, v41 offset:60576
	ds_read_u16 v145, v42 offset:60576
	ds_read_b128 v[148:151], v139 offset:16
	s_waitcnt lgkmcnt(5)
	v_lshlrev_b32_e32 v36, 16, v133
	v_lshlrev_b32_e32 v37, 16, v134
	v_lshlrev_b32_e32 v32, 16, v135
	v_lshlrev_b32_e32 v33, 16, v136
	v_pk_mov_b32 v[34:35], v[32:33], v[36:37] op_sel:[1,0]
	s_nop 0
	v_pk_mul_f32 v[34:35], v[50:51], v[34:35]
	s_nop 0
	v_pk_fma_f32 v[32:33], v[48:49], v[32:33], v[34:35]
	v_lshlrev_b32_e32 v47, 16, v132
	v_pk_fma_f32 v[32:33], v[52:53], v[36:37], v[32:33]
	v_lshlrev_b32_e32 v46, 16, v131
	v_pk_add_f32 v[38:39], v[54:55], v[32:33]
	v_lshlrev_b32_e32 v28, 16, v130
	v_mul_f32_e32 v32, 0xbfb8aa3b, v38
	v_exp_f32_e32 v32, v32
	v_mul_f32_e32 v33, 0xbfb8aa3b, v39
	v_exp_f32_e32 v33, v33
	v_add_f32_e32 v32, 1.0, v32
	v_rcp_f32_e32 v44, v32
	v_add_f32_e32 v32, 1.0, v33
	v_rcp_f32_e32 v45, v32
	v_lshlrev_b32_e32 v29, 16, v129
	s_mul_i32 s78, s78, 0x16c20
	v_pk_mul_f32 v[38:39], v[38:39], v[44:45]
	s_add_i32 s17, s17, 64
	v_pk_mul_f32 v[38:39], v[38:39], s[92:93] op_sel_hi:[1,0]
	s_waitcnt lgkmcnt(4)
	v_add_f32_e32 v115, v30, v138
	v_cvt_pk_bf16_f32 v40, v38, s0
	ds_write_b16 v81, v40 offset:9216
	v_cvt_pk_bf16_f32 v40, v39, s0
	s_waitcnt lgkmcnt(4)
	v_pk_mul_f32 v[38:39], v[140:141], v[38:39]
	v_pk_mov_b32 v[32:33], v[36:37], v[46:47] op_sel:[1,0]
	ds_write_b16 v85, v40 offset:9216
	v_pk_mul_f32 v[32:33], v[50:51], v[32:33]
	s_nop 0
	v_pk_fma_f32 v[32:33], v[48:49], v[36:37], v[32:33]
	v_mov_b32_e32 v42, v29
	v_pk_fma_f32 v[32:33], v[52:53], v[46:47], v[32:33]
	s_waitcnt lgkmcnt(3)
	v_lshlrev_b32_e32 v43, 16, v144
	v_pk_add_f32 v[32:33], v[54:55], v[32:33]
	v_lshlrev_b32_e32 v41, 16, v145
	v_mul_f32_e32 v36, 0xbfb8aa3b, v32
	v_mul_f32_e32 v37, 0xbfb8aa3b, v33
	v_exp_f32_e32 v36, v36
	v_exp_f32_e32 v37, v37
	s_cmpk_eq_i32 s34, 0x84
	s_mov_b32 s29, s34
	v_add_f32_e32 v36, 1.0, v36
	v_add_f32_e32 v37, 1.0, v37
	v_rcp_f32_e32 v36, v36
	v_rcp_f32_e32 v37, v37
	s_nop 0
	v_pk_mul_f32 v[32:33], v[32:33], v[36:37]
	s_nop 0
	v_pk_mul_f32 v[32:33], v[32:33], s[92:93] op_sel_hi:[1,0]
	s_nop 0
	v_cvt_pk_bf16_f32 v36, v32, s0
	ds_write_b16 v85, v36 offset:9360
	v_pk_mov_b32 v[36:37], v[46:47], v[28:29] op_sel:[1,0]
	s_nop 0
	v_pk_mul_f32 v[36:37], v[50:51], v[36:37]
	s_nop 0
	v_pk_fma_f32 v[36:37], v[48:49], v[46:47], v[36:37]
	v_cvt_pk_bf16_f32 v46, v33, s0
	v_pk_fma_f32 v[36:37], v[52:53], v[28:29], v[36:37]
	ds_write_b16 v85, v46 offset:9504
	v_pk_add_f32 v[36:37], v[54:55], v[36:37]
	v_pk_mul_f32 v[46:47], v[142:143], v[32:33]
	v_mul_f32_e32 v40, 0xbfb8aa3b, v36
	v_exp_f32_e32 v40, v40
	v_mul_f32_e32 v44, 0xbfb8aa3b, v37
	v_exp_f32_e32 v45, v44
	v_add_f32_e32 v40, 1.0, v40
	v_rcp_f32_e32 v44, v40
	v_add_f32_e32 v40, 1.0, v45
	v_rcp_f32_e32 v45, v40
	v_mov_b32_e32 v40, v43
	v_pk_mul_f32 v[42:43], v[50:51], v[42:43]
	v_pk_mul_f32 v[36:37], v[36:37], v[44:45]
	v_pk_fma_f32 v[28:29], v[48:49], v[28:29], v[42:43]
	v_pk_mul_f32 v[36:37], v[36:37], s[92:93] op_sel_hi:[1,0]
	v_pk_fma_f32 v[28:29], v[52:53], v[40:41], v[28:29]
	v_cvt_pk_bf16_f32 v44, v36, s0
	v_pk_add_f32 v[28:29], v[54:55], v[28:29]
	s_waitcnt lgkmcnt(4)
	v_pk_mul_f32 v[32:33], v[148:149], v[36:37]
	v_mul_f32_e32 v40, 0xbfb8aa3b, v28
	v_mul_f32_e32 v41, 0xbfb8aa3b, v29
	v_exp_f32_e32 v40, v40
	v_exp_f32_e32 v41, v41
	v_cvt_pk_bf16_f32 v42, v37, s0
	v_cvt_pk_bf16_f32 v30, v32, v33
	v_add_f32_e32 v40, 1.0, v40
	v_add_f32_e32 v41, 1.0, v41
	v_rcp_f32_e32 v40, v40
	v_rcp_f32_e32 v41, v41
	v_add_u32_e32 v32, s78, v93
	ds_write_b16 v85, v44 offset:9648
	ds_write_b16 v85, v42 offset:9792
	v_pk_mul_f32 v[28:29], v[28:29], v[40:41]
	s_nop 0
	v_pk_mul_f32 v[28:29], v[28:29], s[92:93] op_sel_hi:[1,0]
	s_nop 0
	v_cvt_pk_bf16_f32 v36, v28, s0
	v_pk_mul_f32 v[34:35], v[150:151], v[28:29]
	ds_write_b16 v85, v36 offset:9936
	v_cvt_pk_bf16_f32 v36, v29, s0
	v_cvt_pk_bf16_f32 v28, v38, v39
	v_cvt_pk_bf16_f32 v29, v46, v47
	v_cvt_pk_bf16_f32 v31, v34, v35
	ds_write_b16 v85, v36 offset:10080
	ds_write_b128 v32, v[28:31] offset:18432
	s_waitcnt lgkmcnt(0)
	s_barrier
	s_cbranch_scc1 .LBB0_420
.LBB0_406:
	s_and_b32 s35, s29, 1
	s_mul_i32 s30, s35, 0x1f00
	s_lshl_b32 s30, s30, 2
	s_add_i32 s31, s30, 0
	s_add_i32 s30, s31, 0x13220
	s_add_i32 s34, s31, 0x13120
	v_add_u32_e32 v129, v97, v108
	ds_read_b128 v[132:135], v129 offset:9216
	ds_read_b128 v[136:139], v129 offset:9280
	v_lshl_add_u32 v130, v109, 2, s34
	ds_read_b128 v[140:143], v130
	ds_read_b128 v[144:147], v129 offset:48384
	ds_read_b128 v[148:151], v129 offset:48448
	v_add_u32_e32 v131, v97, v110
	ds_read_b128 v[152:155], v131 offset:9280
	ds_read_b128 v[156:159], v131 offset:9216
	ds_read_b128 v[160:163], v130 offset:64
	ds_read_b128 v[164:167], v131 offset:48384
	ds_read_b128 v[172:175], v131 offset:48448
	v_lshl_add_u32 v28, v94, 2, s30
	ds_read_b32 v116, v28
	ds_read_b128 v[40:43], v96
	v_lshl_add_u32 v61, v109, 2, s34
	s_waitcnt lgkmcnt(1)
	v_sub_f32_e32 v28, v115, v116
	v_mul_f32_e32 v28, 0x3fb8aa3b, v28
	v_exp_f32_e32 v60, v28
	ds_read_b128 v[44:47], v96 offset:64
	s_waitcnt lgkmcnt(0)
	v_mfma_f32_16x16x32_bf16 v[28:31], v[132:135], v[40:43], 0
	v_mfma_f32_16x16x32_bf16 v[28:31], v[136:139], v[44:47], v[28:31]
	v_sub_f32_e32 v32, v140, v116
	v_mul_f32_e32 v32, 0x3fb8aa3b, v32
	v_exp_f32_e32 v32, v32
	s_nop 2
	s_nop 1
	v_mul_f32_e32 v28, v28, v32
	v_cndmask_b32_e64 v32, v28, 0, s[60:61]
	v_sub_f32_e32 v28, v141, v116
	v_mul_f32_e32 v28, 0x3fb8aa3b, v28
	v_exp_f32_e32 v28, v28
	s_nop 0
	v_mul_f32_e32 v28, v29, v28
	v_cndmask_b32_e64 v33, 0, v28, s[62:63]
	v_sub_f32_e32 v28, v142, v116
	v_sub_f32_e32 v29, v143, v116
	v_mul_f32_e32 v28, 0x3fb8aa3b, v28
	v_mul_f32_e32 v29, 0x3fb8aa3b, v29
	v_exp_f32_e32 v28, v28
	v_exp_f32_e32 v29, v29
	s_nop 0
	v_pk_mul_f32 v[28:29], v[30:31], v[28:29]
	s_nop 0
	v_cvt_pk_bf16_f32 v28, v28, v29
	v_cndmask_b32_e64 v29, v28, 0, s[66:67]
	v_lshrrev_b32_e32 v28, 16, v28
	v_cndmask_b32_e64 v28, v28, 0, s[64:65]
	v_cvt_pk_bf16_f32 v30, v32, v33
	v_perm_b32 v31, v28, v29, s24
	ds_write_b64 v111, v[30:31] offset:27648
	v_mfma_f32_16x16x32_bf16 v[28:31], v[144:147], v[40:43], 0
	v_mfma_f32_16x16x32_bf16 v[28:31], v[148:151], v[44:47], v[28:31]
	v_mfma_f32_16x16x32_bf16 v[32:35], v[156:159], v[40:43], 0
	s_nop 4
	s_nop 1
	v_mul_f32_e64 v30, v60, v30
	v_mul_f32_e64 v31, v60, v31
	v_pk_mul_f32 v[28:29], v[60:61], v[28:29] op_sel_hi:[0,1]
	v_mfma_f32_16x16x32_bf16 v[32:35], v[152:155], v[44:47], v[32:35]
	v_sub_f32_e32 v36, v160, v116
	v_mul_f32_e32 v36, 0x3fb8aa3b, v36
	v_exp_f32_e32 v36, v36
	s_nop 2
	s_nop 1
	v_mul_f32_e32 v32, v32, v36
	v_cndmask_b32_e64 v36, v32, 0, s[68:69]
	v_sub_f32_e32 v32, v161, v116
	v_mul_f32_e32 v32, 0x3fb8aa3b, v32
	v_exp_f32_e32 v32, v32
	s_nop 0
	v_mul_f32_e32 v32, v33, v32
	v_cndmask_b32_e64 v37, 0, v32, s[70:71]
	v_sub_f32_e32 v32, v162, v116
	v_sub_f32_e32 v33, v163, v116
	v_mul_f32_e32 v32, 0x3fb8aa3b, v32
	v_mul_f32_e32 v33, 0x3fb8aa3b, v33
	v_exp_f32_e32 v32, v32
	v_exp_f32_e32 v33, v33
	s_nop 0
	v_pk_mul_f32 v[32:33], v[34:35], v[32:33]
	s_nop 0
	v_cvt_pk_bf16_f32 v32, v32, v33
	v_cndmask_b32_e64 v33, v32, 0, s[74:75]
	v_lshrrev_b32_e32 v32, 16, v32
	v_cndmask_b32_e64 v32, v32, 0, s[72:73]
	v_cvt_pk_bf16_f32 v34, v36, v37
	v_perm_b32 v35, v32, v33, s24
	ds_write_b64 v112, v[34:35] offset:27648
	v_mfma_f32_16x16x32_bf16 v[32:35], v[164:167], v[40:43], 0
	v_mfma_f32_16x16x32_bf16 v[32:35], v[172:175], v[44:47], v[32:35]
	v_mov_b32_e32 v36, 0
	v_mov_b32_e32 v37, 0
	v_mov_b32_e32 v38, 0
	v_mov_b32_e32 v39, 0
	s_nop 3
	v_pk_mul_f32 v[34:35], v[60:61], v[34:35] op_sel_hi:[0,1]
	v_pk_mul_f32 v[32:33], v[60:61], v[32:33] op_sel_hi:[0,1]
	s_and_saveexec_b64 s[76:77], s[48:49]
	s_cbranch_execz .LBB0_408
	v_add_u32_e32 v61, v104, v95
	ds_read_b128 v[36:39], v61 offset:57600
	s_waitcnt lgkmcnt(0)
	v_mfma_f32_16x16x32_bf16 v[36:39], v[36:39], v[40:43], 0
	ds_read_b128 v[40:43], v61 offset:57664
	v_mov_b32_e32 v61, v60
	s_waitcnt lgkmcnt(0)
	v_mfma_f32_16x16x32_bf16 v[36:39], v[40:43], v[44:47], v[36:39]
	v_mov_b32_e32 v40, v60
	v_mov_b32_e32 v41, v60
	s_nop 5
	v_pk_mul_f32 v[38:39], v[40:41], v[38:39]
	v_pk_mul_f32 v[36:37], v[60:61], v[36:37]

.LBB0_416:
	s_mul_i32 s36, s35, 0xa880
	s_add_i32 s36, s36, 0
	v_add_u32_e32 v60, s36, v95
	v_add_u32_e32 v117, v60, v108
	s_waitcnt lgkmcnt(0)
	s_barrier
	ds_read_b128 v[132:135], v117 offset:36864
	ds_read_b128 v[136:139], v117 offset:36928
	v_add_u32_e32 v129, v60, v110
	ds_read_b128 v[140:143], v129 offset:36864
	ds_read_b128 v[144:147], v129 offset:36928
	ds_read_b128 v[44:47], v96 offset:27648
	ds_read_b128 v[40:43], v96 offset:27712
	v_add_u32_e32 v61, v60, v110
	v_add3_u32 v60, s36, v103, v95
	s_waitcnt lgkmcnt(0)
	v_mfma_f32_16x16x32_bf16 v[28:31], v[132:135], v[44:47], v[28:31]
	v_mfma_f32_16x16x32_bf16 v[28:31], v[136:139], v[40:43], v[28:31]
	v_mfma_f32_16x16x32_bf16 v[32:35], v[140:143], v[44:47], v[32:35]
	v_mfma_f32_16x16x32_bf16 v[32:35], v[144:147], v[40:43], v[32:35]
	s_and_saveexec_b64 s[76:77], s[48:49]
	s_cbranch_execz .LBB0_418
	ds_read_b128 v[118:121], v60 offset:46080
	s_waitcnt lgkmcnt(0)
	v_mfma_f32_16x16x32_bf16 v[36:39], v[118:121], v[44:47], v[36:39]
	ds_read_b128 v[44:47], v60 offset:46144
	s_waitcnt lgkmcnt(0)
	v_mfma_f32_16x16x32_bf16 v[36:39], v[44:47], v[40:43], v[36:39]
	s_nop 7
	ds_write_b32 v113, v36
.LBB0_418:
	s_or_b64 exec, exec, s[76:77]
	s_xor_b32 s78, s35, 1
	s_mul_i32 s76, s35, 0x16c20
	s_mul_i32 s35, s78, 0x7b80
	s_add_i32 s77, s35, 0
	v_add_u32_e32 v129, s77, v79
	v_add_u32_e32 v130, v129, v80
	ds_read_u16 v131, v130 offset:59904
	ds_read_u16 v132, v130 offset:60176
	ds_read_u16 v133, v130 offset:60448
	v_add_u32_e32 v134, s77, v84
	v_add_u32_e32 v135, v134, v80
	ds_read_u16 v136, v135 offset:60448
	v_add_u32_e32 v137, s77, v86
	v_add_u32_e32 v138, v137, v80
	ds_read_u16 v139, v138 offset:60448
	v_add_u32_e32 v140, s77, v87
	v_add_u32_e32 v141, v140, v80
	ds_read_u16 v142, v141 offset:60448
	v_add_u32_e32 v143, s77, v88
	v_add_u32_e32 v144, v143, v80
	ds_read_u16 v145, v144 offset:60448
	v_add_u32_e32 v146, s77, v89
	v_add_u32_e32 v147, v146, v80
	ds_read_u16 v148, v147 offset:60448
	v_add_u32_e32 v149, s77, v90
	v_add_u32_e32 v150, v149, v80
	ds_read_u16 v151, v150 offset:60448
	v_add_u32_e32 v152, s77, v91
	v_add_u32_e32 v153, v152, v80
	ds_read_u16 v154, v153 offset:60448
	v_add_u32_e32 v36, s77, v79
	v_add_u32_e32 v36, v36, v80
	v_lshl_add_u32 v47, v94, 2, s31
	s_add_i32 s35, s17, 0xffffff00
	s_waitcnt lgkmcnt(7)
	v_lshlrev_b32_e32 v37, 16, v131
	v_lshlrev_b32_e32 v38, 16, v132
	v_mul_f32_e32 v40, v64, v38
	v_lshlrev_b32_e32 v39, 16, v133
	v_fmac_f32_e32 v40, v63, v37
	v_fmac_f32_e32 v40, v65, v39
	v_add_f32_e32 v37, v66, v40
	v_mul_f32_e32 v40, 0xbfb8aa3b, v37
	v_exp_f32_e32 v40, v40
	v_mul_f32_e32 v41, v64, v39
	v_fmac_f32_e32 v41, v63, v38
	s_cmp_lt_u32 s29, 4
	v_add_f32_e32 v40, 1.0, v40
	v_rcp_f32_e32 v40, v40
	s_cselect_b32 s29, s17, s35
	v_mul_f32_e32 v37, v37, v40
	v_cvt_pk_bf16_f32 v37, v37, s0
	ds_write_b16 v81, v37
	v_add_u32_e32 v37, s77, v84
	v_add_u32_e32 v37, v37, v80
	s_waitcnt lgkmcnt(7)
	v_lshlrev_b32_e32 v40, 16, v136
	v_fmac_f32_e32 v41, v65, v40
	v_add_f32_e32 v38, v66, v41
	v_mul_f32_e32 v41, 0xbfb8aa3b, v38
	v_exp_f32_e32 v41, v41
	v_mul_f32_e32 v42, v64, v40
	v_fmac_f32_e32 v42, v63, v39
	v_add_f32_e32 v41, 1.0, v41
	v_rcp_f32_e32 v41, v41
	s_nop 0
	v_mul_f32_e32 v38, v38, v41
	v_cvt_pk_bf16_f32 v38, v38, s0
	ds_write_b16 v85, v38
	v_add_u32_e32 v38, s77, v86
	v_add_u32_e32 v38, v38, v80
	s_waitcnt lgkmcnt(7)
	v_lshlrev_b32_e32 v41, 16, v139
	v_fmac_f32_e32 v42, v65, v41
	v_add_f32_e32 v39, v66, v42
	v_mul_f32_e32 v42, 0xbfb8aa3b, v39
	v_exp_f32_e32 v42, v42
	v_mul_f32_e32 v43, v64, v41
	v_fmac_f32_e32 v43, v63, v40
	v_add_f32_e32 v42, 1.0, v42
	v_rcp_f32_e32 v42, v42
	s_nop 0
	v_mul_f32_e32 v39, v39, v42
	v_cvt_pk_bf16_f32 v39, v39, s0
	ds_write_b16 v85, v39 offset:144
	v_add_u32_e32 v39, s77, v87
	v_add_u32_e32 v39, v39, v80
	s_waitcnt lgkmcnt(7)
	v_lshlrev_b32_e32 v42, 16, v142
	v_fmac_f32_e32 v43, v65, v42
	v_add_f32_e32 v40, v66, v43
	v_mul_f32_e32 v43, 0xbfb8aa3b, v40
	v_exp_f32_e32 v43, v43
	s_nop 0
	v_add_f32_e32 v43, 1.0, v43
	v_rcp_f32_e32 v43, v43
	s_nop 0
	v_mul_f32_e32 v40, v40, v43
	v_cvt_pk_bf16_f32 v40, v40, s0
	ds_write_b16 v85, v40 offset:288
	v_add_u32_e32 v40, s77, v88
	v_add_u32_e32 v40, v40, v80
	s_waitcnt lgkmcnt(7)
	v_lshlrev_b32_e32 v44, 16, v145
	v_mul_f32_e32 v43, v64, v42
	v_fmac_f32_e32 v43, v63, v41
	v_fmac_f32_e32 v43, v65, v44
	v_add_f32_e32 v41, v66, v43
	v_mul_f32_e32 v43, 0xbfb8aa3b, v41
	v_exp_f32_e32 v43, v43
	s_nop 0
	v_add_f32_e32 v43, 1.0, v43
	v_rcp_f32_e32 v43, v43
	s_nop 0
	v_mul_f32_e32 v41, v41, v43
	v_cvt_pk_bf16_f32 v41, v41, s0
	ds_write_b16 v85, v41 offset:432
	v_add_u32_e32 v41, s77, v89
	v_add_u32_e32 v43, v41, v80
	s_waitcnt lgkmcnt(7)
	v_lshlrev_b32_e32 v45, 16, v148
	v_mul_f32_e32 v41, v64, v44
	v_fmac_f32_e32 v41, v63, v42
	v_fmac_f32_e32 v41, v65, v45
	v_add_f32_e32 v41, v66, v41
	v_mul_f32_e32 v42, 0xbfb8aa3b, v41
	v_exp_f32_e32 v42, v42
	s_nop 0
	v_add_f32_e32 v42, 1.0, v42
	v_rcp_f32_e32 v42, v42
	s_nop 0
	v_mul_f32_e32 v41, v41, v42
	v_cvt_pk_bf16_f32 v41, v41, s0
	ds_write_b16 v85, v41 offset:576
	v_add_u32_e32 v41, s77, v90
	v_add_u32_e32 v41, v41, v80
	s_waitcnt lgkmcnt(7)
	v_lshlrev_b32_e32 v46, 16, v151
	v_mul_f32_e32 v42, v64, v45
	v_fmac_f32_e32 v42, v63, v44
	v_fmac_f32_e32 v42, v65, v46
	v_add_f32_e32 v42, v66, v42
	v_mul_f32_e32 v44, 0xbfb8aa3b, v42
	v_exp_f32_e32 v44, v44
	v_mul_f32_e32 v46, v64, v46
	v_fmac_f32_e32 v46, v63, v45
	v_add_f32_e32 v44, 1.0, v44
	v_rcp_f32_e32 v44, v44
	s_nop 0
	v_mul_f32_e32 v42, v42, v44
	v_cvt_pk_bf16_f32 v42, v42, s0
	ds_write_b16 v85, v42 offset:720
	v_add_u32_e32 v42, s77, v91
	v_add_u32_e32 v42, v42, v80
	s_waitcnt lgkmcnt(7)
	v_lshlrev_b32_e32 v44, 16, v154
	v_fmac_f32_e32 v46, v65, v44
	v_add_f32_e32 v44, v66, v46
	v_mul_f32_e32 v45, 0xbfb8aa3b, v44
	v_exp_f32_e32 v45, v45
	s_nop 0
	v_add_f32_e32 v45, 1.0, v45
	v_rcp_f32_e32 v45, v45
	s_nop 0
	v_mul_f32_e32 v44, v44, v45
	v_cvt_pk_bf16_f32 v44, v44, s0
	ds_write_b16 v85, v44 offset:864
	s_waitcnt lgkmcnt(0)
	s_barrier
	ds_read_b32 v129, v102
	ds_read_b32 v130, v47
	v_add_u32_e32 v131, s76, v96
	ds_read_b128 v[132:135], v131 offset:18432
	ds_read_b128 v[136:139], v117 offset:36864
	ds_read_b128 v[140:143], v131 offset:18496
	ds_read_b128 v[144:147], v117 offset:36928
	ds_read_b128 v[148:151], v131 offset:18432
	ds_read_b128 v[152:155], v61 offset:36864
	ds_read_b128 v[156:159], v131 offset:18496
	ds_read_b128 v[160:163], v61 offset:36928
	v_add_u32_e32 v44, s29, v94
	s_cselect_b32 s29, 0xff, s22
	v_sub_u32_e32 v45, s29, v44
	s_waitcnt lgkmcnt(8)
	v_max_f32_e64 v46, |v129|, |v129|
	v_add_f32_e32 v47, v116, v130
	v_mul_f32_e32 v47, 0xbfb8aa3b, v47
	v_exp_f32_e32 v47, v47
	v_cndmask_b32_e64 v44, v45, v44, s[40:41]
	s_cselect_b32 s29, s16, s28
	v_add_u32_e32 v44, s29, v44
	v_max_f32_e32 v46, v46, v47
	v_rcp_f32_e32 v46, v46
	v_ashrrev_i32_e32 v45, 31, v44
	v_lshlrev_b64 v[44:45], 11, v[44:45]
	v_pk_mul_f32 v[28:29], v[28:29], v[46:47] op_sel_hi:[1,0]
	v_pk_mul_f32 v[30:31], v[30:31], v[46:47] op_sel_hi:[1,0]
	v_cvt_pk_bf16_f32 v28, v28, v29
	v_cvt_pk_bf16_f32 v29, v30, v31
	v_lshl_add_u64 v[30:31], v[58:59], 0, v[44:45]
	global_store_dwordx2 v[30:31], v[28:29], off offset:1024
	v_pk_mul_f32 v[28:29], v[32:33], v[46:47] op_sel_hi:[1,0]
	v_pk_mul_f32 v[32:33], v[34:35], v[46:47] op_sel_hi:[1,0]
	v_cvt_pk_bf16_f32 v28, v28, v29
	v_cvt_pk_bf16_f32 v29, v32, v33
	global_store_dwordx2 v[30:31], v[28:29], off offset:1056
	v_mov_b32_e32 v28, s30
	ds_read_b32 v30, v28 offset:252
	v_add_u32_e32 v31, s76, v96
	s_waitcnt lgkmcnt(0)
	v_sub_f32_e32 v28, v115, v30
	v_mul_f32_e32 v28, 0x3fb8aa3b, v28
	v_exp_f32_e32 v28, v28
	s_nop 0
	v_pk_mul_f32 v[26:27], v[26:27], v[28:29] op_sel_hi:[1,0]
	v_pk_mul_f32 v[24:25], v[24:25], v[28:29] op_sel_hi:[1,0]
	v_add_u32_e32 v29, v107, v108
	v_pk_mul_f32 v[18:19], v[18:19], v[28:29] op_sel_hi:[1,0]
	v_mfma_f32_16x16x32_bf16 v[24:27], v[132:135], v[136:139], v[24:27]
	v_pk_mul_f32 v[16:17], v[16:17], v[28:29] op_sel_hi:[1,0]
	v_mfma_f32_16x16x32_bf16 v[24:27], v[140:143], v[144:147], v[24:27]
	s_nop 7
	v_cvt_pk_bf16_f32 v32, v24, v25
	v_cvt_pk_bf16_f32 v33, v26, v27
	ds_write_b64 v29, v[32:33] offset:48384
	v_mfma_f32_16x16x32_bf16 v[16:19], v[148:151], v[152:155], v[16:19]
	v_add_u32_e32 v29, v107, v110
	v_mfma_f32_16x16x32_bf16 v[16:19], v[156:159], v[160:163], v[16:19]
	s_nop 7
	v_cvt_pk_bf16_f32 v32, v16, v17
	v_cvt_pk_bf16_f32 v33, v18, v19
	ds_write_b64 v29, v[32:33] offset:48384
	s_and_saveexec_b64 s[76:77], s[48:49]
	s_cbranch_execz .LBB0_405
	v_mov_b32_e32 v32, v28
	v_mov_b32_e32 v33, v28
	v_pk_mul_f32 v[22:23], v[32:33], v[22:23]
	ds_read_b128 v[32:35], v31 offset:18432
	ds_read_b128 v[44:47], v60 offset:46080
	v_mov_b32_e32 v29, v28
	v_pk_mul_f32 v[20:21], v[28:29], v[20:21]
	s_waitcnt lgkmcnt(0)
	s_nop 0
	v_mfma_f32_16x16x32_bf16 v[20:23], v[32:35], v[44:47], v[20:23]
	ds_read_b128 v[32:35], v31 offset:18496
	ds_read_b128 v[44:47], v60 offset:46144
	s_waitcnt lgkmcnt(0)
	v_mfma_f32_16x16x32_bf16 v[20:23], v[32:35], v[44:47], v[20:23]
	s_nop 7
	v_cvt_pk_bf16_f32 v28, v20, v21
	v_cvt_pk_bf16_f32 v29, v22, v23
	ds_write_b64 v114, v[28:29] offset:57600
	s_branch .LBB0_405

.LBB0_442:
	s_mul_i32 s16, s34, 0x18920
	s_xor_b32 s74, s34, 1
	s_mul_i32 s17, s74, 0x6b00
	s_add_i32 s34, s17, 0
	ds_read_b128 v[132:135], v99 offset:36864
	ds_read_b128 v[136:139], v99 offset:36928
	v_add_u32_e32 v129, s16, v100
	v_add_u32_e32 v130, v129, v107
	ds_read_b128 v[140:143], v130 offset:18432
	ds_read_b128 v[144:147], v130 offset:18496
	ds_read_b64 v[148:149], v109 offset:55296
	v_add_u32_e32 v131, v129, v108
	ds_read_b128 v[152:155], v131 offset:18432
	ds_read_b128 v[156:159], v131 offset:18496
	ds_read_b64 v[150:151], v110 offset:55296
	v_mul_f32_e32 v61, 0x3fb8aa3b, v61
	v_exp_f32_e32 v112, v61
	v_ashrrev_i32_e32 v61, 31, v60
	v_lshlrev_b64 v[60:61], 11, v[60:61]
	v_lshl_add_u64 v[124:125], s[8:9], 0, v[60:61]
	v_add_u32_e32 v60, s16, v100
	v_add_u32_e32 v61, v60, v107
	v_pk_mul_f32 v[26:27], v[112:113], v[26:27] op_sel_hi:[0,1]
	v_pk_mul_f32 v[24:25], v[112:113], v[24:25] op_sel_hi:[0,1]
	v_pk_mul_f32 v[30:31], v[112:113], v[30:31] op_sel_hi:[0,1]
	v_pk_mul_f32 v[28:29], v[112:113], v[28:29] op_sel_hi:[0,1]
	s_waitcnt lgkmcnt(4)
	v_mfma_f32_16x16x32_bf16 v[24:27], v[140:143], v[132:135], v[24:27]
	v_add_u32_e32 v60, v60, v108
	v_mfma_f32_16x16x32_bf16 v[24:27], v[144:147], v[136:139], v[24:27]
	v_add3_u32 v111, s34, v82, v83
	v_add_u32_e32 v128, 0xfc00, v111
	s_waitcnt lgkmcnt(3)
	v_lshlrev_b32_e32 v122, 16, v148
	v_and_b32_e32 v123, 0xffff0000, v148
	v_lshlrev_b32_e32 v120, 16, v149
	v_and_b32_e32 v121, 0xffff0000, v149
	s_nop 0
	v_pk_fma_f32 v[24:25], v[46:47], v[122:123], v[24:25]
	v_pk_fma_f32 v[26:27], v[46:47], v[120:121], v[26:27]
	v_cvt_pk_bf16_f32 v24, v24, v25
	v_cvt_pk_bf16_f32 v25, v26, v27
	v_lshl_add_u64 v[120:121], v[124:125], 0, v[168:169]
	global_store_dwordx2 v[120:121], v[24:25], off offset:512
	s_waitcnt lgkmcnt(1)
	v_mfma_f32_16x16x32_bf16 v[24:27], v[152:155], v[132:135], v[28:31]
	s_nop 2
	v_add_u32_e32 v124, s17, v85
	v_add3_u32 v112, s34, v86, v83
	v_mfma_f32_16x16x32_bf16 v[24:27], v[156:159], v[136:139], v[24:27]
	ds_read_u16 v160, v111 offset:64640
	ds_read_u16 v161, v111 offset:65440
	ds_read_u16 v162, v111 offset:65040
	ds_read_b128 v[164:167], v124
	ds_read_u16 v163, v112 offset:65440
	v_add3_u32 v172, s34, v89, v83
	ds_read_u16 v173, v172 offset:65440
	v_add3_u32 v174, s34, v90, v83
	ds_read_u16 v175, v174 offset:65440
	v_add3_u32 v176, s34, v91, v83
	ds_read_u16 v177, v176 offset:65440
	ds_read_b128 v[180:183], v124 offset:16
	v_add3_u32 v178, s34, v93, v83
	ds_read_u16 v179, v178 offset:65440
	v_add3_u32 v184, s34, v92, v83
	ds_read_u16 v185, v184 offset:65440
	v_add3_u32 v186, s34, v94, v83
	ds_read_u16 v187, v186 offset:65440
	ds_read_u16 v188, v111 offset:65168
	ds_read_u16 v189, v128 offset:1056
	ds_read_u16 v190, v111 offset:64768
	v_add_u32_e32 v191, 0x10020, v112
	ds_read_u16 v192, v191
	v_add_u32_e32 v193, 0x10020, v172
	ds_read_u16 v194, v193
	v_add_u32_e32 v195, 0x10020, v174
	ds_read_u16 v196, v195
	v_add_u32_e32 v197, 0x10020, v176
	ds_read_u16 v198, v197
	v_add_u32_e32 v199, 0x10020, v184
	ds_read_u16 v200, v199
	v_add_u32_e32 v201, 0x10020, v178
	ds_read_u16 v202, v201
	v_add_u32_e32 v203, 0x10020, v186
	ds_read_u16 v204, v203
	v_add3_u32 v113, s34, v89, v83
	s_mul_i32 s74, s74, 0x18920
	s_add_i32 s29, s29, 64
	s_cmpk_eq_i32 s31, 0x84
	s_waitcnt lgkmcnt(12)
	v_lshlrev_b32_e32 v30, 16, v150
	v_and_b32_e32 v31, 0xffff0000, v150
	v_lshlrev_b32_e32 v28, 16, v151
	v_and_b32_e32 v29, 0xffff0000, v151
	v_pk_fma_f32 v[24:25], v[46:47], v[30:31], v[24:25]
	v_pk_fma_f32 v[26:27], v[46:47], v[28:29], v[26:27]
	v_cvt_pk_bf16_f32 v24, v24, v25
	v_cvt_pk_bf16_f32 v25, v26, v27
	global_store_dwordx2 v[120:121], v[24:25], off offset:544
	s_mov_b32 s35, s31
	v_lshlrev_b32_e32 v30, 16, v161
	v_lshlrev_b32_e32 v31, 16, v162
	v_pk_mul_f32 v[114:115], v[42:43], v[30:31]
	v_lshlrev_b32_e32 v24, 16, v160
	v_mul_f32_e32 v27, v43, v30
	v_mov_b32_e32 v25, v31
	v_mov_b32_e32 v26, v115
	v_pk_fma_f32 v[116:117], v[40:41], v[24:25], v[26:27]
	v_lshlrev_b32_e32 v28, 16, v163
	v_mul_f32_e32 v115, v42, v28
	v_pk_add_f32 v[114:115], v[114:115], v[116:117]
	v_lshlrev_b32_e32 v29, 16, v173
	v_pk_add_f32 v[114:115], v[44:45], v[114:115]
	v_mul_f32_e32 v119, v43, v29
	v_mul_f32_e32 v31, 0xbfb8aa3b, v114
	v_exp_f32_e32 v31, v31
	s_nop 0
	v_add_f32_e32 v31, 1.0, v31
	v_rcp_f32_e32 v116, v31
	v_mul_f32_e32 v31, 0xbfb8aa3b, v115
	v_exp_f32_e32 v31, v31
	s_nop 0
	v_add_f32_e32 v31, 1.0, v31
	v_rcp_f32_e32 v117, v31
	s_nop 0
	v_pk_mul_f32 v[114:115], v[114:115], v[116:117]
	s_nop 0
	v_cvt_pk_bf16_f32 v31, v114, s0
	ds_write_b16 v84, v31 offset:9216
	v_cvt_pk_bf16_f32 v31, v115, s0
	v_pk_mul_f32 v[116:117], v[58:59], v[28:29]
	v_pk_mul_f32 v[24:25], v[164:165], v[114:115]
	ds_write_b16 v87, v31 offset:9216
	v_add3_u32 v114, s34, v90, v83
	v_mov_b32_e32 v31, v28
	v_mov_b32_e32 v118, v116
	v_pk_fma_f32 v[30:31], v[40:41], v[30:31], v[118:119]
	v_add3_u32 v115, s34, v91, v83
	v_cvt_pk_bf16_f32 v24, v24, v25
	v_lshlrev_b32_e32 v120, 16, v175
	v_lshlrev_b32_e32 v121, 16, v177
	v_mul_f32_e32 v119, v42, v120
	v_mov_b32_e32 v118, v117
	v_pk_add_f32 v[30:31], v[30:31], v[118:119]
	v_pk_mul_f32 v[118:119], v[58:59], v[120:121]
	v_pk_add_f32 v[30:31], v[44:45], v[30:31]
	v_pk_mov_b32 v[28:29], v[28:29], v[120:121] op_sel:[1,0]
	v_mul_f32_e32 v116, 0xbfb8aa3b, v30
	v_mul_f32_e32 v117, 0xbfb8aa3b, v31
	v_exp_f32_e32 v116, v116
	v_exp_f32_e32 v117, v117
	v_mov_b32_e32 v126, v119
	v_add_f32_e32 v116, 1.0, v116
	v_add_f32_e32 v117, 1.0, v117
	v_rcp_f32_e32 v116, v116
	v_rcp_f32_e32 v117, v117
	s_nop 0
	v_pk_mul_f32 v[30:31], v[30:31], v[116:117]
	s_nop 0
	v_cvt_pk_bf16_f32 v116, v30, s0
	v_pk_mul_f32 v[26:27], v[166:167], v[30:31]
	v_cvt_pk_bf16_f32 v30, v31, s0
	ds_write_b16 v87, v116 offset:9360
	ds_write_b16 v87, v30 offset:9504
	v_mul_f32_e32 v31, v43, v121
	v_mov_b32_e32 v30, v118
	v_add3_u32 v117, s34, v93, v83
	v_add3_u32 v116, s34, v92, v83
	v_pk_fma_f32 v[122:123], v[40:41], v[28:29], v[30:31]
	v_cvt_pk_bf16_f32 v25, v26, v27
	v_lshlrev_b32_e32 v125, 16, v179
	s_waitcnt lgkmcnt(12)
	v_lshlrev_b32_e32 v124, 16, v185
	v_mul_f32_e32 v127, v42, v124
	v_pk_add_f32 v[118:119], v[122:123], v[126:127]
	s_nop 0
	v_pk_add_f32 v[118:119], v[44:45], v[118:119]
	s_nop 0
	v_mul_f32_e32 v122, 0xbfb8aa3b, v118
	v_mul_f32_e32 v123, 0xbfb8aa3b, v119
	v_exp_f32_e32 v122, v122
	v_exp_f32_e32 v123, v123
	v_add_f32_e32 v122, 1.0, v122
	v_add_f32_e32 v123, 1.0, v123
	v_rcp_f32_e32 v122, v122
	v_rcp_f32_e32 v123, v123
	s_nop 0
	v_pk_mul_f32 v[118:119], v[118:119], v[122:123]
	s_nop 0
	v_cvt_pk_bf16_f32 v122, v118, s0
	v_pk_mul_f32 v[28:29], v[180:181], v[118:119]
	v_cvt_pk_bf16_f32 v118, v119, s0
	ds_write_b16 v87, v122 offset:9648
	ds_write_b16 v87, v118 offset:9792
	v_add3_u32 v118, s34, v94, v83
	v_pk_mul_f32 v[122:123], v[58:59], v[124:125]
	v_mul_f32_e32 v125, v43, v125
	v_pk_mov_b32 v[120:121], v[120:121], v[124:125] op_sel:[1,0]
	v_mov_b32_e32 v124, v122
	v_lshlrev_b32_e32 v119, 16, v187
	v_mul_f32_e32 v127, v42, v119
	v_pk_fma_f32 v[120:121], v[40:41], v[120:121], v[124:125]
	v_mov_b32_e32 v126, v123
	v_pk_add_f32 v[120:121], v[120:121], v[126:127]
	v_cvt_pk_bf16_f32 v26, v28, v29
	v_pk_add_f32 v[120:121], v[44:45], v[120:121]
	s_nop 0
	v_mul_f32_e32 v119, 0xbfb8aa3b, v120
	v_exp_f32_e32 v119, v119
	s_nop 0
	v_add_f32_e32 v119, 1.0, v119
	v_rcp_f32_e32 v122, v119
	v_mul_f32_e32 v119, 0xbfb8aa3b, v121
	v_exp_f32_e32 v119, v119
	s_nop 0
	v_add_f32_e32 v119, 1.0, v119
	v_rcp_f32_e32 v123, v119
	s_nop 0
	v_pk_mul_f32 v[120:121], v[120:121], v[122:123]
	s_nop 0
	v_cvt_pk_bf16_f32 v119, v120, s0
	ds_write_b16 v87, v119 offset:9936
	v_cvt_pk_bf16_f32 v119, v121, s0
	v_pk_mul_f32 v[30:31], v[182:183], v[120:121]
	ds_write_b16 v87, v119 offset:10080
	v_cvt_pk_bf16_f32 v27, v30, v31
	v_lshlrev_b32_e32 v119, 16, v188
	v_lshlrev_b32_e32 v120, 16, v189
	s_waitcnt lgkmcnt(12)
	v_lshlrev_b32_e32 v121, 16, v190
	v_mul_f32_e32 v121, v63, v121
	v_fmac_f32_e32 v121, v64, v119
	v_fmac_f32_e32 v121, v65, v120
	v_add_f32_e32 v121, v66, v121
	v_mul_f32_e32 v122, 0xbfb8aa3b, v121
	v_exp_f32_e32 v122, v122
	v_mul_f32_e32 v119, v63, v119
	v_fmac_f32_e32 v119, v64, v120
	v_add_f32_e32 v122, 1.0, v122
	v_rcp_f32_e32 v122, v122
	s_nop 0
	v_mul_f32_e32 v121, v121, v122
	v_cvt_pk_bf16_f32 v121, v121, s0
	ds_write_b16 v84, v121
	v_lshlrev_b32_e32 v121, 16, v192
	v_fmac_f32_e32 v119, v65, v121
	v_add_f32_e32 v119, v66, v119
	v_mul_f32_e32 v122, 0xbfb8aa3b, v119
	v_exp_f32_e32 v122, v122
	s_nop 0
	v_add_f32_e32 v122, 1.0, v122
	v_rcp_f32_e32 v122, v122
	s_nop 0
	v_mul_f32_e32 v119, v119, v122
	v_cvt_pk_bf16_f32 v119, v119, s0
	ds_write_b16 v87, v119
	v_mul_f32_e32 v122, v64, v121
	v_fmac_f32_e32 v122, v63, v120
	v_lshlrev_b32_e32 v119, 16, v194
	v_fmac_f32_e32 v122, v65, v119
	v_add_f32_e32 v120, v66, v122
	v_mul_f32_e32 v122, 0xbfb8aa3b, v120
	v_exp_f32_e32 v122, v122
	s_nop 0
	v_add_f32_e32 v122, 1.0, v122
	v_rcp_f32_e32 v122, v122
	s_nop 0
	v_mul_f32_e32 v120, v120, v122
	v_cvt_pk_bf16_f32 v120, v120, s0
	ds_write_b16 v87, v120 offset:144
	v_mul_f32_e32 v122, v64, v119
	v_fmac_f32_e32 v122, v63, v121
	v_lshlrev_b32_e32 v120, 16, v196
	v_fmac_f32_e32 v122, v65, v120
	v_add_f32_e32 v121, v66, v122
	v_mul_f32_e32 v122, 0xbfb8aa3b, v121
	v_exp_f32_e32 v122, v122
	s_nop 0
	v_add_f32_e32 v122, 1.0, v122
	v_rcp_f32_e32 v122, v122
	s_nop 0
	v_mul_f32_e32 v121, v121, v122
	v_cvt_pk_bf16_f32 v121, v121, s0
	ds_write_b16 v87, v121 offset:288
	v_mul_f32_e32 v122, v64, v120
	v_fmac_f32_e32 v122, v63, v119
	s_waitcnt lgkmcnt(12)
	v_lshlrev_b32_e32 v121, 16, v198
	v_fmac_f32_e32 v122, v65, v121
	v_add_f32_e32 v119, v66, v122
	v_mul_f32_e32 v122, 0xbfb8aa3b, v119
	v_exp_f32_e32 v122, v122
	s_nop 0
	v_add_f32_e32 v122, 1.0, v122
	v_rcp_f32_e32 v122, v122
	s_nop 0
	v_mul_f32_e32 v119, v119, v122
	v_cvt_pk_bf16_f32 v119, v119, s0
	ds_write_b16 v87, v119 offset:432
	v_mul_f32_e32 v122, v64, v121
	v_fmac_f32_e32 v122, v63, v120
	v_lshlrev_b32_e32 v119, 16, v200
	v_fmac_f32_e32 v122, v65, v119
	v_add_f32_e32 v120, v66, v122
	v_mul_f32_e32 v122, 0xbfb8aa3b, v120
	v_exp_f32_e32 v122, v122
	s_nop 0
	v_add_f32_e32 v122, 1.0, v122
	v_rcp_f32_e32 v122, v122
	s_nop 0
	v_mul_f32_e32 v120, v120, v122
	v_cvt_pk_bf16_f32 v120, v120, s0
	ds_write_b16 v87, v120 offset:576
	v_mul_f32_e32 v122, v64, v119
	v_fmac_f32_e32 v122, v63, v121
	v_lshlrev_b32_e32 v120, 16, v202
	v_fmac_f32_e32 v122, v65, v120
	v_add_f32_e32 v121, v66, v122
	v_mul_f32_e32 v122, 0xbfb8aa3b, v121
	v_exp_f32_e32 v122, v122
	v_mul_f32_e32 v120, v64, v120
	v_fmac_f32_e32 v120, v63, v119
	v_add_f32_e32 v122, 1.0, v122
	v_rcp_f32_e32 v122, v122
	s_nop 0
	v_mul_f32_e32 v121, v121, v122
	v_cvt_pk_bf16_f32 v121, v121, s0
	ds_write_b16 v87, v121 offset:720
	v_add_u32_e32 v121, s16, v99
	v_lshlrev_b32_e32 v119, 16, v204
	v_fmac_f32_e32 v120, v65, v119
	v_add_f32_e32 v119, v66, v120
	v_mul_f32_e32 v120, 0xbfb8aa3b, v119
	v_exp_f32_e32 v120, v120
	s_nop 0
	v_add_f32_e32 v120, 1.0, v120
	v_rcp_f32_e32 v120, v120
	s_nop 0
	v_mul_f32_e32 v119, v119, v120
	v_cvt_pk_bf16_f32 v119, v119, s0
	ds_write_b16 v87, v119 offset:864
	v_add_u32_e32 v119, s74, v49
	ds_write_b128 v119, v[24:27] offset:27648
	v_mov_b32_e32 v24, s84
	s_waitcnt lgkmcnt(0)
	s_barrier
	ds_read_b32 v129, v24 offset:252
	ds_read_b128 v[132:135], v121 offset:27648
	ds_read_b128 v[136:139], v61 offset:18432
	ds_read_b128 v[140:143], v121 offset:27712
	ds_read_b128 v[144:147], v61 offset:18496
	ds_read_b128 v[148:151], v121 offset:27648
	ds_read_b128 v[152:155], v60 offset:18432
	ds_read_b128 v[156:159], v121 offset:27712
	ds_read_b128 v[160:163], v60 offset:18496
	s_waitcnt lgkmcnt(8)
	v_mul_f32_e32 v24, 0x3fb8aa3b, v129
	v_exp_f32_e32 v120, v24
	s_nop 0
	v_pk_mul_f32 v[18:19], v[18:19], v[120:121] op_sel_hi:[1,0]
	v_pk_mul_f32 v[16:17], v[16:17], v[120:121] op_sel_hi:[1,0]
	v_pk_mul_f32 v[22:23], v[22:23], v[120:121] op_sel_hi:[1,0]
	v_pk_mul_f32 v[20:21], v[20:21], v[120:121] op_sel_hi:[1,0]
	s_waitcnt lgkmcnt(4)
	v_mfma_f32_16x16x32_bf16 v[16:19], v[132:135], v[136:139], v[16:19]
	v_mfma_f32_16x16x32_bf16 v[16:19], v[140:143], v[144:147], v[16:19]
	v_add_u32_e32 v26, v106, v107
	s_nop 6
	v_cvt_pk_bf16_f32 v24, v16, v17
	v_cvt_pk_bf16_f32 v25, v18, v19
	ds_write_b64 v26, v[24:25] offset:46080
	s_waitcnt lgkmcnt(1)
	v_mfma_f32_16x16x32_bf16 v[20:23], v[148:151], v[152:155], v[20:23]
	v_mfma_f32_16x16x32_bf16 v[20:23], v[156:159], v[160:163], v[20:23]
	ds_read_u16 v130, v115 offset:65312
	ds_read_u16 v131, v116 offset:65312
	ds_read_u16 v164, v117 offset:65312
	ds_read_u16 v165, v118 offset:65312
	ds_read_u16 v166, v113 offset:65312
	ds_read_u16 v167, v114 offset:65312
	ds_read_u16 v172, v111 offset:65312
	ds_read_u16 v173, v112 offset:65312
	ds_read_u16 v174, v111 offset:64512
	ds_read_u16 v175, v111 offset:64912
	v_add_u32_e32 v176, s17, v96
	ds_read_b128 v[180:183], v176
	ds_read_b128 v[184:187], v176 offset:16
	v_add_u32_e32 v26, v106, v108
	s_nop 6
	v_cvt_pk_bf16_f32 v24, v20, v21
	v_cvt_pk_bf16_f32 v25, v22, v23
	ds_write_b64 v26, v[24:25] offset:46080
	s_waitcnt lgkmcnt(9)
	v_lshlrev_b32_e32 v28, 16, v130
	v_lshlrev_b32_e32 v29, 16, v131
	v_mov_b32_e32 v60, v29
	v_lshlrev_b32_e32 v61, 16, v164
	v_lshlrev_b32_e32 v31, 16, v165
	s_waitcnt lgkmcnt(4)
	v_lshlrev_b32_e32 v116, 16, v166
	v_lshlrev_b32_e32 v117, 16, v167
	v_lshlrev_b32_e32 v120, 16, v172
	v_lshlrev_b32_e32 v121, 16, v173
	v_lshlrev_b32_e32 v122, 16, v174
	s_waitcnt lgkmcnt(3)
	v_lshlrev_b32_e32 v123, 16, v175
	v_pk_mov_b32 v[124:125], v[122:123], v[120:121] op_sel:[1,0]
	s_nop 0
	v_pk_mul_f32 v[124:125], v[34:35], v[124:125]
	s_nop 0
	v_pk_fma_f32 v[122:123], v[32:33], v[122:123], v[124:125]
	s_nop 0
	v_pk_fma_f32 v[122:123], v[36:37], v[120:121], v[122:123]
	s_nop 0
	v_pk_add_f32 v[122:123], v[38:39], v[122:123]
	s_nop 0
	v_mul_f32_e32 v30, 0xbfb8aa3b, v122
	v_exp_f32_e32 v30, v30
	s_nop 0
	v_add_f32_e32 v30, 1.0, v30
	v_rcp_f32_e32 v124, v30
	v_mul_f32_e32 v30, 0xbfb8aa3b, v123
	v_exp_f32_e32 v30, v30
	s_nop 0
	v_add_f32_e32 v30, 1.0, v30
	v_rcp_f32_e32 v125, v30
	s_nop 0
	v_pk_mul_f32 v[122:123], v[122:123], v[124:125]
	s_nop 0
	v_cvt_pk_bf16_f32 v30, v122, s0
	ds_write_b16 v95, v30 offset:55296
	v_cvt_pk_bf16_f32 v30, v123, s0
	s_waitcnt lgkmcnt(3)
	v_pk_mul_f32 v[112:113], v[180:181], v[122:123]
	v_pk_mov_b32 v[122:123], v[120:121], v[116:117] op_sel:[1,0]
	ds_write_b16 v97, v30 offset:55296
	v_pk_mul_f32 v[122:123], v[34:35], v[122:123]
	s_nop 0
	v_pk_fma_f32 v[120:121], v[32:33], v[120:121], v[122:123]
	s_nop 0
	v_pk_fma_f32 v[120:121], v[36:37], v[116:117], v[120:121]
	s_nop 0
	v_pk_add_f32 v[120:121], v[38:39], v[120:121]
	s_nop 0
	v_mul_f32_e32 v30, 0xbfb8aa3b, v120
	v_exp_f32_e32 v30, v30
	s_nop 0
	v_add_f32_e32 v30, 1.0, v30
	v_rcp_f32_e32 v122, v30
	v_mul_f32_e32 v30, 0xbfb8aa3b, v121
	v_exp_f32_e32 v30, v30
	s_nop 0
	v_add_f32_e32 v30, 1.0, v30
	v_rcp_f32_e32 v123, v30
	s_nop 0
	v_pk_mul_f32 v[120:121], v[120:121], v[122:123]
	s_nop 0
	v_cvt_pk_bf16_f32 v30, v120, s0
	ds_write_b16 v97, v30 offset:55440
	v_cvt_pk_bf16_f32 v30, v121, s0
	v_pk_mul_f32 v[114:115], v[182:183], v[120:121]
	v_pk_mov_b32 v[120:121], v[116:117], v[28:29] op_sel:[1,0]
	ds_write_b16 v97, v30 offset:55584
	v_pk_mul_f32 v[120:121], v[34:35], v[120:121]
	s_nop 0
	v_pk_fma_f32 v[116:117], v[32:33], v[116:117], v[120:121]
	s_nop 0
	v_pk_fma_f32 v[116:117], v[36:37], v[28:29], v[116:117]
	s_nop 0
	v_pk_add_f32 v[116:117], v[38:39], v[116:117]
	s_nop 0
	v_mul_f32_e32 v30, 0xbfb8aa3b, v116
	v_exp_f32_e32 v30, v30
	s_nop 0
	v_add_f32_e32 v30, 1.0, v30
	v_rcp_f32_e32 v120, v30
	v_mul_f32_e32 v30, 0xbfb8aa3b, v117
	v_exp_f32_e32 v30, v30
	s_nop 0
	v_add_f32_e32 v30, 1.0, v30
	v_rcp_f32_e32 v121, v30
	s_nop 0
	v_pk_mul_f32 v[116:117], v[116:117], v[120:121]
	s_nop 0
	v_cvt_pk_bf16_f32 v30, v116, s0
	ds_write_b16 v97, v30 offset:55728
	v_cvt_pk_bf16_f32 v30, v117, s0
	s_waitcnt lgkmcnt(6)
	v_pk_mul_f32 v[116:117], v[184:185], v[116:117]
	v_pk_mul_f32 v[24:25], v[34:35], v[60:61]
	ds_write_b16 v97, v30 offset:55872
	v_mov_b32_e32 v30, v61
	v_pk_fma_f32 v[24:25], v[32:33], v[28:29], v[24:25]
	s_nop 0
	v_pk_fma_f32 v[24:25], v[36:37], v[30:31], v[24:25]
	s_nop 0
	v_pk_add_f32 v[24:25], v[38:39], v[24:25]
	s_nop 0
	v_mul_f32_e32 v28, 0xbfb8aa3b, v24
	v_mul_f32_e32 v29, 0xbfb8aa3b, v25
	v_exp_f32_e32 v28, v28
	v_exp_f32_e32 v29, v29
	v_add_f32_e32 v28, 1.0, v28
	v_add_f32_e32 v29, 1.0, v29
	v_rcp_f32_e32 v28, v28
	v_rcp_f32_e32 v29, v29
	s_nop 0
	v_pk_mul_f32 v[24:25], v[24:25], v[28:29]
	s_nop 0
	v_cvt_pk_bf16_f32 v28, v24, s0
	ds_write_b16 v97, v28 offset:56016
	v_cvt_pk_bf16_f32 v28, v25, s0
	ds_write_b16 v97, v28 offset:56160
	v_pk_mul_f32 v[28:29], v[186:187], v[24:25]
	v_cvt_pk_bf16_f32 v24, v112, v113
	v_cvt_pk_bf16_f32 v25, v114, v115
	v_cvt_pk_bf16_f32 v26, v116, v117
	v_cvt_pk_bf16_f32 v27, v28, v29
	ds_write_b128 v119, v[24:27] offset:18432
	s_waitcnt lgkmcnt(0)
	s_barrier
	s_cbranch_scc1 .LBB0_474
.LBB0_443:
	s_and_b32 s34, s35, 1
	s_mul_i32 s16, s34, 0x6b00
	s_add_i32 s84, s16, 0
	s_add_i32 s84, s84, 0x16320
	ds_read_b128 v[132:135], v99
	v_add_u32_e32 v129, v100, v107
	ds_read_b128 v[136:139], v129 offset:9216
	ds_read_b128 v[140:143], v99 offset:64
	ds_read_b128 v[144:147], v129 offset:9280
	v_lshl_add_u32 v130, v48, 2, s84
	ds_read_b128 v[148:151], v130
	ds_read_b128 v[152:155], v129 offset:46080
	ds_read_b128 v[156:159], v129 offset:46144
	v_add_u32_e32 v131, v100, v108
	ds_read_b128 v[160:163], v131 offset:9280
	ds_read_b128 v[164:167], v131 offset:9216
	ds_read_b128 v[172:175], v130 offset:64
	ds_read_b128 v[176:179], v131 offset:46080
	ds_read_b128 v[180:183], v131 offset:46144
	v_lshl_add_u32 v24, v98, 2, s84
	ds_read_b32 v61, v24
	s_add_i32 s31, s35, 1
	s_cmpk_eq_i32 s35, 0x83
	s_waitcnt lgkmcnt(0)
	v_mfma_f32_16x16x32_bf16 v[24:27], v[136:139], v[132:135], 0
	v_mfma_f32_16x16x32_bf16 v[24:27], v[144:147], v[140:143], v[24:27]
	v_sub_f32_e32 v116, v61, v148
	v_mul_f32_e32 v116, 0x3fb8aa3b, v116
	v_exp_f32_e32 v116, v116
	s_nop 2
	s_nop 1
	v_mul_f32_e32 v24, v24, v116
	v_cndmask_b32_e64 v116, v24, 0, s[58:59]
	v_sub_f32_e32 v24, v61, v149
	v_mul_f32_e32 v24, 0x3fb8aa3b, v24
	v_exp_f32_e32 v24, v24
	s_nop 0
	v_mul_f32_e32 v24, v25, v24
	v_cndmask_b32_e64 v117, 0, v24, s[60:61]
	v_sub_f32_e32 v24, v61, v150
	v_sub_f32_e32 v25, v61, v151
	v_mul_f32_e32 v24, 0x3fb8aa3b, v24
	v_mul_f32_e32 v25, 0x3fb8aa3b, v25
	v_exp_f32_e32 v24, v24
	v_exp_f32_e32 v25, v25
	s_nop 0
	v_pk_mul_f32 v[24:25], v[26:27], v[24:25]
	s_nop 0
	v_cvt_pk_bf16_f32 v24, v24, v25
	v_cndmask_b32_e64 v25, v24, 0, s[64:65]
	v_lshrrev_b32_e32 v24, 16, v24
	v_cndmask_b32_e64 v24, v24, 0, s[62:63]
	v_cvt_pk_bf16_f32 v26, v116, v117
	v_perm_b32 v27, v24, v25, s24
	ds_write_b64 v109, v[26:27] offset:36864
	v_mfma_f32_16x16x32_bf16 v[24:27], v[152:155], v[132:135], 0
	v_mfma_f32_16x16x32_bf16 v[24:27], v[156:159], v[140:143], v[24:27]
	v_mfma_f32_16x16x32_bf16 v[116:119], v[164:167], v[132:135], 0
	v_mfma_f32_16x16x32_bf16 v[116:119], v[160:163], v[140:143], v[116:119]
	v_sub_f32_e32 v111, v61, v172
	v_mul_f32_e32 v111, 0x3fb8aa3b, v111
	v_exp_f32_e32 v111, v111
	s_nop 2
	s_nop 1
	v_mul_f32_e32 v111, v116, v111
	v_sub_f32_e32 v116, v61, v173
	v_mul_f32_e32 v116, 0x3fb8aa3b, v116
	v_exp_f32_e32 v116, v116
	v_cndmask_b32_e64 v111, v111, 0, s[66:67]
	v_mul_f32_e32 v116, v117, v116
	v_cndmask_b32_e64 v120, 0, v116, s[68:69]
	v_sub_f32_e32 v116, v61, v174
	v_sub_f32_e32 v117, v61, v175
	v_mul_f32_e32 v116, 0x3fb8aa3b, v116
	v_mul_f32_e32 v117, 0x3fb8aa3b, v117
	v_exp_f32_e32 v116, v116
	v_exp_f32_e32 v117, v117
	s_nop 0
	v_pk_mul_f32 v[116:117], v[118:119], v[116:117]
	v_cvt_pk_bf16_f32 v118, v111, v120
	v_cvt_pk_bf16_f32 v111, v116, v117
	v_cndmask_b32_e64 v116, v111, 0, s[72:73]
	v_lshrrev_b32_e32 v111, 16, v111
	v_cndmask_b32_e64 v111, v111, 0, s[70:71]
	v_perm_b32 v119, v111, v116, s24
	ds_write_b64 v110, v[118:119] offset:36864
	v_mfma_f32_16x16x32_bf16 v[28:31], v[176:179], v[132:135], 0
	v_mfma_f32_16x16x32_bf16 v[28:31], v[180:183], v[140:143], v[28:31]
	s_cbranch_scc1 .LBB0_470
	s_xor_b32 s16, s34, 1
	s_mulk_i32 s16, 0x6b00
	s_add_i32 s17, s16, 0
	v_add_u32_e32 v60, s17, v71
	v_add3_u32 v60, v60, v72, v73
	s_waitcnt vmcnt(0)
	s_waitcnt vmcnt(4)
	ds_write_b128 v60, v[0:3] offset:64912
	v_add_u32_e32 v60, s17, v74
	v_add3_u32 v60, v60, v75, v76
	s_waitcnt vmcnt(3)
	ds_write_b128 v60, v[4:7] offset:64912
	v_add_u32_e32 v60, s17, v77
	v_add3_u32 v60, v60, v78, v79
	s_waitcnt vmcnt(2)
	ds_write_b128 v60, v[8:11] offset:64912
	s_and_saveexec_b64 s[78:79], s[42:43]
	s_cbranch_execz .LBB0_447
	s_add_i32 s36, s35, -3
	s_cmp_gt_u32 s35, 2
	s_cselect_b32 s36, s36, s31
	s_cselect_b32 s37, 0x2000, s23
	v_lshl_add_u32 v60, s36, 6, v104
	v_cmp_lt_i32_e32 vcc, -1, v60
	v_cmp_gt_i32_e64 s[74:75], s37, v60
	s_and_b64 vcc, vcc, s[74:75]
	v_add_u32_e32 v60, s17, v105
	s_waitcnt vmcnt(1)
	v_cndmask_b32_e32 v115, 0, v15, vcc
	v_cndmask_b32_e32 v114, 0, v14, vcc
	v_cndmask_b32_e32 v113, 0, v13, vcc
	v_cndmask_b32_e32 v112, 0, v12, vcc
	v_add3_u32 v60, v60, v72, v73
	ds_write_b128 v60, v[112:115] offset:64512
	s_or_b64 exec, exec, s[78:79]
	s_and_saveexec_b64 s[74:75], s[44:45]
	s_cbranch_execnz .LBB0_448

.LBB0_488:
	ds_read_b128 v[132:135], v65 offset:27648
	v_add_u32_e32 v129, v66, v71
	ds_read_b128 v[136:139], v129 offset:36864
	ds_read_b128 v[140:143], v65 offset:27712
	ds_read_b128 v[144:147], v129 offset:36928
	ds_read_b128 v[148:151], v129 offset:64512
	ds_read_b128 v[152:155], v129 offset:64576
	v_add_u32_e32 v130, v66, v72
	ds_read_b128 v[156:159], v130 offset:36864
	ds_read_b128 v[160:163], v130 offset:64512
	ds_read_b128 v[164:167], v130 offset:64576
	s_and_b32 s35, s29, 1
	s_cmpk_eq_i32 s29, 0x83
	s_waitcnt lgkmcnt(5)
	v_mfma_f32_16x16x32_bf16 v[28:31], v[136:139], v[132:135], 0
	v_mfma_f32_16x16x32_bf16 v[28:31], v[144:147], v[140:143], v[28:31]
	s_nop 7
	v_cndmask_b32_e64 v28, v28, 0, s[60:61]
	v_cndmask_b32_e64 v29, 0, v29, s[62:63]
	v_cndmask_b32_e64 v30, v30, 0, s[64:65]
	v_cndmask_b32_e64 v31, v31, 0, s[66:67]
	v_cvt_pk_bf16_f32 v28, v28, v29
	v_cvt_pk_bf16_f32 v29, v30, v31
	ds_write_b64 v73, v[28:29] offset:55296
	s_waitcnt lgkmcnt(5)
	v_mfma_f32_16x16x32_bf16 v[28:31], v[148:151], v[132:135], 0
	v_add_u32_e32 v75, v66, v72
	ds_read_b128 v[84:87], v75 offset:36928
	s_waitcnt lgkmcnt(0)
	v_mfma_f32_16x16x32_bf16 v[28:31], v[152:155], v[140:143], v[28:31]
	v_mfma_f32_16x16x32_bf16 v[80:83], v[156:159], v[132:135], 0
	v_mfma_f32_16x16x32_bf16 v[80:83], v[84:87], v[140:143], v[80:83]
	s_nop 7
	v_cndmask_b32_e64 v80, v80, 0, s[68:69]
	v_cndmask_b32_e64 v81, 0, v81, s[70:71]
	v_cndmask_b32_e64 v82, v82, 0, s[72:73]
	v_cndmask_b32_e64 v83, v83, 0, s[74:75]
	v_cvt_pk_bf16_f32 v80, v80, v81
	v_cvt_pk_bf16_f32 v81, v82, v83
	ds_write_b64 v74, v[80:81] offset:55296
	v_mfma_f32_16x16x32_bf16 v[24:27], v[160:163], v[132:135], 0
	v_mfma_f32_16x16x32_bf16 v[24:27], v[164:167], v[140:143], v[24:27]
	s_cbranch_scc1 .LBB0_493
	s_xor_b32 s30, s35, 1
	s_mul_i32 s31, s30, 0x13a00
	s_waitcnt vmcnt(0)
	v_add_u32_e32 v75, s31, v57
	s_waitcnt vmcnt(3)
	ds_write_b128 v75, v[0:3]
	s_waitcnt vmcnt(2)
	ds_write_b128 v75, v[4:7] offset:9216
	v_add_u32_e32 v75, s31, v58
	s_mul_i32 s34, s30, 0x8600
	s_waitcnt vmcnt(1)
	ds_write_b16 v75, v8 offset:18432
	ds_write_b16_d16_hi v75, v8 offset:18576
	ds_write_b16 v75, v9 offset:18720
	ds_write_b16_d16_hi v75, v9 offset:18864
	ds_write_b16 v75, v10 offset:19008
	ds_write_b16_d16_hi v75, v10 offset:19152
	ds_write_b16 v75, v11 offset:19296
	ds_write_b16_d16_hi v75, v11 offset:19440
	s_and_saveexec_b64 s[8:9], s[40:41]
	s_cbranch_execz .LBB0_491
	v_add_u32_e32 v75, s34, v68
	s_waitcnt vmcnt(0)
	ds_write_b128 v75, v[12:15]

.LBB0_494:
	s_add_i32 s37, s16, 0xffffff00
	s_cmp_lt_u32 s29, 4
	s_mul_i32 s36, s35, 0x13a00
	s_mul_i32 s8, s35, 0x10200
	s_mul_i32 s9, s35, 0xa200
	s_cselect_b32 s35, s16, s37
	v_add_u32_e32 v75, s35, v64
	s_cselect_b32 s35, 0xff, s22
	v_sub_u32_e32 v76, s35, v75
	v_cndmask_b32_e32 v75, v76, v75, vcc
	s_cselect_b32 s35, s28, s17
	v_add_u32_e32 v76, s35, v75
	v_add_u32_e32 v90, s36, v66
	v_ashrrev_i32_e32 v77, 31, v76
	v_add_u32_e32 v75, v90, v71
	s_waitcnt lgkmcnt(0)
	s_barrier
	ds_read_b128 v[132:135], v65 offset:55296
	ds_read_b128 v[136:139], v65 offset:55360
	ds_read_b128 v[140:143], v75 offset:18432
	ds_read_b128 v[144:147], v75 offset:18496
	v_add_u32_e32 v129, v90, v72
	ds_read_b128 v[148:151], v129 offset:18432
	ds_read_b128 v[152:155], v129 offset:18496
	v_add_u32_e32 v131, s34, v59
	ds_read2_b32 v[172:173], v131 offset0:0 offset1:4
	ds_read2_b32 v[174:175], v131 offset0:1 offset1:5
	ds_read2_b32 v[176:177], v131 offset0:2 offset1:6
	ds_read2_b32 v[178:179], v131 offset0:3 offset1:7
	ds_read2_b32 v[180:181], v131 offset0:8 offset1:12
	ds_read2_b32 v[182:183], v131 offset0:9 offset1:13
	ds_read2_b32 v[184:185], v131 offset0:10 offset1:14
	ds_read2_b32 v[186:187], v131 offset0:11 offset1:15
	ds_read2_b32 v[188:189], v131 offset0:16 offset1:20
	ds_read2_b32 v[190:191], v131 offset0:17 offset1:21
	ds_read2_b32 v[192:193], v131 offset0:18 offset1:22
	ds_read2_b32 v[194:195], v131 offset0:19 offset1:23
	ds_read2_b32 v[196:197], v131 offset0:24 offset1:28
	ds_read2_b32 v[198:199], v131 offset0:25 offset1:29
	ds_read2_b32 v[200:201], v131 offset0:26 offset1:30
	ds_read2_b32 v[202:203], v131 offset0:27 offset1:31
	ds_read2_b32 v[204:205], v131 offset0:32 offset1:36
	ds_read2_b32 v[206:207], v131 offset0:33 offset1:37
	ds_read2_b32 v[208:209], v131 offset0:34 offset1:38
	ds_read2_b32 v[210:211], v131 offset0:35 offset1:39
	ds_read2_b32 v[212:213], v131 offset0:40 offset1:44
	ds_read2_b32 v[214:215], v131 offset0:41 offset1:45
	ds_read2_b32 v[216:217], v131 offset0:42 offset1:46
	ds_read2_b32 v[218:219], v131 offset0:43 offset1:47
	v_lshlrev_b64 v[88:89], 11, v[76:77]
	s_waitcnt lgkmcnt(12)
	v_mfma_f32_16x16x32_bf16 v[28:31], v[140:143], v[132:135], v[28:31]
	v_mfma_f32_16x16x32_bf16 v[28:31], v[144:147], v[136:139], v[28:31]
	s_nop 7
	v_cvt_pk_bf16_f32 v28, v28, v29
	v_cvt_pk_bf16_f32 v29, v30, v31
	v_lshl_add_u64 v[30:31], v[52:53], 0, v[88:89]
	global_store_dwordx2 v[30:31], v[28:29], off
	v_add_u32_e32 v28, v90, v72
	v_mfma_f32_16x16x32_bf16 v[24:27], v[148:151], v[132:135], v[24:27]
	v_mfma_f32_16x16x32_bf16 v[24:27], v[152:155], v[136:139], v[24:27]
	s_nop 7
	v_cvt_pk_bf16_f32 v24, v24, v25
	v_cvt_pk_bf16_f32 v25, v26, v27
	global_store_dwordx2 v[30:31], v[24:25], off offset:32
	v_pk_mul_f32 v[156:157], v[34:35], v[174:175]
	v_pk_mul_f32 v[158:159], v[42:43], v[182:183]
	v_pk_fma_f32 v[156:157], v[32:33], v[172:173], v[156:157]
	v_pk_fma_f32 v[158:159], v[40:41], v[180:181], v[158:159]
	v_pk_fma_f32 v[156:157], v[36:37], v[176:177], v[156:157]
	v_pk_fma_f32 v[158:159], v[44:45], v[184:185], v[158:159]
	v_pk_fma_f32 v[156:157], v[38:39], v[178:179], v[156:157]
	v_pk_fma_f32 v[158:159], v[46:47], v[186:187], v[158:159]
	ds_read2_b32 v[172:173], v131 offset0:48 offset1:52
	ds_read2_b32 v[174:175], v131 offset0:49 offset1:53
	ds_read2_b32 v[176:177], v131 offset0:50 offset1:54
	ds_read2_b32 v[178:179], v131 offset0:51 offset1:55
	ds_read2_b32 v[180:181], v131 offset0:56 offset1:60
	ds_read2_b32 v[182:183], v131 offset0:57 offset1:61
	ds_read2_b32 v[184:185], v131 offset0:58 offset1:62
	ds_read2_b32 v[186:187], v131 offset0:59 offset1:63
	v_add_f32_e32 v164, v54, v156
	v_pk_mul_f32 v[160:161], v[34:35], v[190:191]
	s_waitcnt lgkmcnt(12)
	v_pk_mul_f32 v[162:163], v[42:43], v[198:199]
	v_add_f32_e32 v164, v164, v157
	v_pk_fma_f32 v[160:161], v[32:33], v[188:189], v[160:161]
	v_pk_fma_f32 v[162:163], v[40:41], v[196:197], v[162:163]
	v_add_f32_e32 v164, v164, v158
	v_pk_fma_f32 v[160:161], v[36:37], v[192:193], v[160:161]
	v_pk_fma_f32 v[162:163], v[44:45], v[200:201], v[162:163]
	v_add_f32_e32 v164, v164, v159
	v_pk_fma_f32 v[160:161], v[38:39], v[194:195], v[160:161]
	v_min_f32_e32 v166, 0, v164
	v_pk_fma_f32 v[162:163], v[46:47], v[202:203], v[162:163]
	v_mul_f32_e64 v164, |v164|, s19
	ds_read2_b32 v[188:189], v131 offset0:64 offset1:68
	v_exp_f32_e32 v164, v164
	ds_read2_b32 v[190:191], v131 offset0:65 offset1:69
	ds_read2_b32 v[192:193], v131 offset0:66 offset1:70
	v_add_f32_e32 v164, 1.0, v164
	ds_read2_b32 v[194:195], v131 offset0:67 offset1:71
	v_log_f32_e32 v164, v164
	ds_read2_b32 v[196:197], v131 offset0:72 offset1:76
	ds_read2_b32 v[198:199], v131 offset0:73 offset1:77
	v_fmac_f32_e32 v166, 0xbf317218, v164
	ds_read2_b32 v[200:201], v131 offset0:74 offset1:78
	v_fma_f32 v25, v166, s26, 0
	ds_read2_b32 v[202:203], v131 offset0:75 offset1:79
	v_add_f32_e32 v165, v54, v160
	v_pk_mul_f32 v[156:157], v[34:35], v[206:207]
	s_waitcnt lgkmcnt(12)
	v_pk_mul_f32 v[158:159], v[42:43], v[214:215]
	v_add_f32_e32 v165, v165, v161
	v_pk_fma_f32 v[156:157], v[32:33], v[204:205], v[156:157]
	v_pk_fma_f32 v[158:159], v[40:41], v[212:213], v[158:159]
	v_add_f32_e32 v165, v165, v162
	v_pk_fma_f32 v[156:157], v[36:37], v[208:209], v[156:157]
	v_pk_fma_f32 v[158:159], v[44:45], v[216:217], v[158:159]
	v_add_f32_e32 v165, v165, v163
	v_pk_fma_f32 v[156:157], v[38:39], v[210:211], v[156:157]
	v_min_f32_e32 v167, 0, v165
	v_pk_fma_f32 v[158:159], v[46:47], v[218:219], v[158:159]
	v_mul_f32_e64 v165, |v165|, s19
	ds_read2_b32 v[204:205], v131 offset0:80 offset1:84
	v_exp_f32_e32 v165, v165
	ds_read2_b32 v[206:207], v131 offset0:81 offset1:85
	ds_read2_b32 v[208:209], v131 offset0:82 offset1:86
	v_add_f32_e32 v165, 1.0, v165
	ds_read2_b32 v[210:211], v131 offset0:83 offset1:87
	v_log_f32_e32 v165, v165
	ds_read2_b32 v[212:213], v131 offset0:88 offset1:92
	ds_read2_b32 v[214:215], v131 offset0:89 offset1:93
	v_fmac_f32_e32 v167, 0xbf317218, v165
	ds_read2_b32 v[216:217], v131 offset0:90 offset1:94
	v_fmamk_f32 v26, v167, 0x3d800000, v25
	ds_read2_b32 v[218:219], v131 offset0:91 offset1:95
	v_add_f32_e32 v164, v54, v156
	v_pk_mul_f32 v[160:161], v[34:35], v[174:175]
	s_waitcnt lgkmcnt(12)
	v_pk_mul_f32 v[162:163], v[42:43], v[182:183]
	v_add_f32_e32 v164, v164, v157
	v_pk_fma_f32 v[160:161], v[32:33], v[172:173], v[160:161]
	v_pk_fma_f32 v[162:163], v[40:41], v[180:181], v[162:163]
	v_add_f32_e32 v164, v164, v158
	v_pk_fma_f32 v[160:161], v[36:37], v[176:177], v[160:161]
	v_pk_fma_f32 v[162:163], v[44:45], v[184:185], v[162:163]
	v_add_f32_e32 v164, v164, v159
	v_pk_fma_f32 v[160:161], v[38:39], v[178:179], v[160:161]
	v_min_f32_e32 v166, 0, v164
	v_pk_fma_f32 v[162:163], v[46:47], v[186:187], v[162:163]
	v_mul_f32_e64 v164, |v164|, s19
	ds_read2_b32 v[172:173], v131 offset0:96 offset1:100
	v_exp_f32_e32 v164, v164
	ds_read2_b32 v[174:175], v131 offset0:97 offset1:101
	ds_read2_b32 v[176:177], v131 offset0:98 offset1:102
	v_add_f32_e32 v164, 1.0, v164
	ds_read2_b32 v[178:179], v131 offset0:99 offset1:103
	v_log_f32_e32 v164, v164
	ds_read2_b32 v[180:181], v131 offset0:104 offset1:108
	ds_read2_b32 v[182:183], v131 offset0:105 offset1:109
	v_fmac_f32_e32 v166, 0xbf317218, v164
	ds_read2_b32 v[184:185], v131 offset0:106 offset1:110
	v_fmamk_f32 v29, v166, 0x3d800000, v26
	ds_read2_b32 v[186:187], v131 offset0:107 offset1:111
	v_add_f32_e32 v165, v54, v160
	v_pk_mul_f32 v[156:157], v[34:35], v[190:191]
	s_waitcnt lgkmcnt(12)
	v_pk_mul_f32 v[158:159], v[42:43], v[198:199]
	v_add_f32_e32 v165, v165, v161
	v_pk_fma_f32 v[156:157], v[32:33], v[188:189], v[156:157]
	v_pk_fma_f32 v[158:159], v[40:41], v[196:197], v[158:159]
	v_add_f32_e32 v165, v165, v162
	v_pk_fma_f32 v[156:157], v[36:37], v[192:193], v[156:157]
	v_pk_fma_f32 v[158:159], v[44:45], v[200:201], v[158:159]
	v_add_f32_e32 v165, v165, v163
	v_pk_fma_f32 v[156:157], v[38:39], v[194:195], v[156:157]
	v_min_f32_e32 v167, 0, v165
	v_pk_fma_f32 v[158:159], v[46:47], v[202:203], v[158:159]
	v_mul_f32_e64 v165, |v165|, s19
	ds_read2_b32 v[188:189], v131 offset0:112 offset1:116
	v_exp_f32_e32 v165, v165
	ds_read2_b32 v[190:191], v131 offset0:113 offset1:117
	ds_read2_b32 v[192:193], v131 offset0:114 offset1:118
	v_add_f32_e32 v165, 1.0, v165
	ds_read2_b32 v[194:195], v131 offset0:115 offset1:119
	v_log_f32_e32 v165, v165
	ds_read2_b32 v[196:197], v131 offset0:120 offset1:124
	ds_read2_b32 v[198:199], v131 offset0:121 offset1:125
	v_fmac_f32_e32 v167, 0xbf317218, v165
	ds_read2_b32 v[200:201], v131 offset0:122 offset1:126
	v_fmamk_f32 v30, v167, 0x3d800000, v29
	ds_read2_b32 v[202:203], v131 offset0:123 offset1:127
	v_add_f32_e32 v164, v54, v156
	v_pk_mul_f32 v[160:161], v[34:35], v[206:207]
	v_add_f32_e32 v164, v164, v157
	s_waitcnt lgkmcnt(12)
	v_pk_mul_f32 v[162:163], v[42:43], v[214:215]
	v_add_f32_e32 v164, v164, v158
	v_pk_fma_f32 v[160:161], v[32:33], v[204:205], v[160:161]
	v_add_f32_e32 v164, v164, v159
	v_pk_fma_f32 v[162:163], v[40:41], v[212:213], v[162:163]
	v_min_f32_e32 v166, 0, v164
	v_pk_fma_f32 v[160:161], v[36:37], v[208:209], v[160:161]
	v_mul_f32_e64 v164, |v164|, s19
	v_pk_fma_f32 v[162:163], v[44:45], v[216:217], v[162:163]
	v_exp_f32_e32 v164, v164
	v_pk_fma_f32 v[160:161], v[38:39], v[210:211], v[160:161]
	v_pk_fma_f32 v[162:163], v[46:47], v[218:219], v[162:163]
	v_add_f32_e32 v164, 1.0, v164
	v_log_f32_e32 v164, v164
	s_nop 0
	v_fmac_f32_e32 v166, 0xbf317218, v164
	v_fmamk_f32 v31, v166, 0x3d800000, v30
	v_add_f32_e32 v165, v54, v160
	v_pk_mul_f32 v[156:157], v[34:35], v[174:175]
	v_add_f32_e32 v165, v165, v161
	s_waitcnt lgkmcnt(10)
	v_pk_mul_f32 v[158:159], v[42:43], v[182:183]
	v_add_f32_e32 v165, v165, v162
	v_pk_fma_f32 v[156:157], v[32:33], v[172:173], v[156:157]
	v_add_f32_e32 v165, v165, v163
	v_pk_fma_f32 v[158:159], v[40:41], v[180:181], v[158:159]
	v_min_f32_e32 v167, 0, v165
	v_pk_fma_f32 v[156:157], v[36:37], v[176:177], v[156:157]
	v_mul_f32_e64 v165, |v165|, s19
	s_waitcnt lgkmcnt(8)
	v_pk_fma_f32 v[158:159], v[44:45], v[184:185], v[158:159]
	v_exp_f32_e32 v165, v165
	v_pk_fma_f32 v[156:157], v[38:39], v[178:179], v[156:157]
	v_pk_fma_f32 v[158:159], v[46:47], v[186:187], v[158:159]
	v_add_f32_e32 v165, 1.0, v165
	v_log_f32_e32 v165, v165
	s_nop 0
	v_fmac_f32_e32 v167, 0xbf317218, v165
	v_fmamk_f32 v76, v167, 0x3d800000, v31
	v_add_f32_e32 v164, v54, v156
	s_waitcnt lgkmcnt(2)
	v_pk_mul_f32 v[160:161], v[34:35], v[190:191]
	v_add_f32_e32 v164, v164, v157
	v_pk_mul_f32 v[162:163], v[42:43], v[198:199]
	v_add_f32_e32 v164, v164, v158
	v_pk_fma_f32 v[160:161], v[32:33], v[188:189], v[160:161]
	v_add_f32_e32 v164, v164, v159
	v_pk_fma_f32 v[162:163], v[40:41], v[196:197], v[162:163]
	v_min_f32_e32 v166, 0, v164
	v_pk_fma_f32 v[160:161], v[36:37], v[192:193], v[160:161]
	v_mul_f32_e64 v164, |v164|, s19
	s_waitcnt lgkmcnt(0)
	v_pk_fma_f32 v[162:163], v[44:45], v[200:201], v[162:163]
	v_exp_f32_e32 v164, v164
	v_pk_fma_f32 v[160:161], v[38:39], v[194:195], v[160:161]
	v_pk_fma_f32 v[162:163], v[46:47], v[202:203], v[162:163]
	v_add_f32_e32 v164, 1.0, v164
	v_log_f32_e32 v164, v164
	s_nop 0
	v_fmac_f32_e32 v166, 0xbf317218, v164
	v_fmamk_f32 v77, v166, 0x3d800000, v76
	v_add_f32_e32 v165, v54, v160
	v_add_f32_e32 v165, v165, v161
	v_add_f32_e32 v165, v165, v162
	v_add_f32_e32 v165, v165, v163
	v_min_f32_e32 v167, 0, v165
	v_mul_f32_e64 v165, |v165|, s19
	v_exp_f32_e32 v165, v165
	s_nop 0
	v_add_f32_e32 v165, 1.0, v165
	v_log_f32_e32 v165, v165
	s_nop 0
	v_fmac_f32_e32 v167, 0xbf317218, v165
	v_fmamk_f32 v78, v167, 0x3d800000, v77
	v_add_u32_e32 v79, s31, v62
	v_add_u32_e32 v24, s9, v69
	ds_write_b32 v60, v78
	s_waitcnt lgkmcnt(0)
	s_barrier
	ds_read_b128 v[132:135], v24
	v_add_u32_e32 v129, s8, v65
	ds_read_b128 v[136:139], v129 offset:46080
	ds_read_b128 v[140:143], v75 offset:18432
	ds_read_b128 v[144:147], v129 offset:46144
	ds_read_b128 v[148:151], v75 offset:18496
	ds_read_b128 v[152:155], v129 offset:46080
	ds_read_b128 v[156:159], v28 offset:18432
	ds_read_b128 v[160:163], v129 offset:46144
	ds_read_b128 v[164:167], v28 offset:18496
	v_add_u32_e32 v27, v70, v71
	s_mul_i32 s8, s30, 0x10200
	s_waitcnt lgkmcnt(6)
	v_pk_mul_f32 v[16:17], v[16:17], v[132:133]
	v_pk_mul_f32 v[18:19], v[18:19], v[134:135]
	v_pk_mul_f32 v[20:21], v[20:21], v[132:133]
	v_pk_mul_f32 v[22:23], v[22:23], v[134:135]
	v_mfma_f32_16x16x32_bf16 v[16:19], v[136:139], v[140:143], v[16:19]
	s_waitcnt lgkmcnt(4)
	v_mfma_f32_16x16x32_bf16 v[16:19], v[144:147], v[148:151], v[16:19]
	s_nop 7
	v_cvt_pk_bf16_f32 v84, v16, v17
	v_cvt_pk_bf16_f32 v85, v18, v19
	ds_write_b64 v27, v[84:85] offset:64512
	s_waitcnt lgkmcnt(1)
	v_mfma_f32_16x16x32_bf16 v[20:23], v[152:155], v[156:159], v[20:23]
	v_add_u32_e32 v24, v70, v72
	v_mfma_f32_16x16x32_bf16 v[20:23], v[160:163], v[164:167], v[20:23]
	ds_read2st64_b32 v[130:131], v61 offset1:1
	ds_read2st64_b32 v[172:173], v61 offset0:2 offset1:3
	ds_read2st64_b32 v[174:175], v61 offset0:4 offset1:5
	ds_read2st64_b32 v[176:177], v61 offset0:6 offset1:7
	ds_read_u16 v178, v79
	ds_read_u16 v179, v79 offset:9216
	ds_read_u16 v180, v79 offset:144
	ds_read_u16 v181, v79 offset:9360
	ds_read_u16 v182, v79 offset:288
	ds_read_u16 v183, v79 offset:9504
	ds_read_u16 v184, v79 offset:432
	ds_read_u16 v185, v79 offset:9648
	ds_read_u16 v186, v79 offset:576
	ds_read_u16 v187, v79 offset:9792
	ds_read_u16 v188, v79 offset:720
	ds_read_u16 v189, v79 offset:9936
	ds_read_u16 v190, v79 offset:864
	ds_read_u16 v191, v79 offset:10080
	ds_read_u16 v192, v79 offset:1008
	ds_read_u16 v193, v79 offset:10224
	s_nop 7
	v_cvt_pk_bf16_f32 v80, v20, v21
	v_cvt_pk_bf16_f32 v81, v22, v23
	ds_write_b64 v24, v[80:81] offset:64512
	s_waitcnt lgkmcnt(12)
	v_add_f32_e32 v24, 0, v130
	v_cndmask_b32_e64 v27, 0, v24, s[42:43]
	v_add_f32_e32 v28, v131, v27
	v_add_f32_e32 v24, v24, v131
	v_cndmask_b32_e64 v27, v27, v28, s[44:45]
	v_add_f32_e32 v28, v172, v27
	v_cndmask_b32_e64 v27, v27, v28, s[46:47]
	v_add_f32_e32 v24, v24, v172
	v_add_f32_e32 v28, v173, v27
	v_add_f32_e32 v24, v24, v173
	v_cndmask_b32_e64 v27, v27, v28, s[48:49]
	v_add_f32_e32 v28, v174, v27
	v_cndmask_b32_e64 v27, v27, v28, s[50:51]
	v_add_f32_e32 v24, v24, v174
	v_add_f32_e32 v28, v175, v27
	v_add_f32_e32 v24, v24, v175
	v_cndmask_b32_e64 v27, v27, v28, s[52:53]
	v_add_f32_e32 v28, v176, v27
	v_cndmask_b32_e64 v27, v27, v28, s[54:55]
	v_add_f32_e32 v28, v177, v27
	v_cndmask_b32_e64 v75, v27, v28, s[56:57]
	v_add_f32_e32 v25, v25, v75
	v_mul_f32_e32 v27, 0xbfb8aa3b, v25
	v_add_f32_e32 v24, v24, v176
	v_exp_f32_e32 v80, v27
	v_mul_f32_e32 v25, 0x3fb8aa3b, v25
	v_exp_f32_e32 v25, v25
	v_add_f32_e32 v24, v24, v177
	v_lshlrev_b32_e32 v27, 16, v178
	v_mul_f32_e32 v27, 0x3e000000, v27
	v_mul_f32_e32 v25, v27, v25
	v_cvt_pk_bf16_f32 v25, v25, s0
	ds_write_b16 v62, v25 offset:27648
	v_add_f32_e32 v25, v26, v75
	v_lshlrev_b32_e32 v82, 16, v179
	v_mul_f32_e32 v26, 0xbfb8aa3b, v25
	v_exp_f32_e32 v81, v26
	v_mul_f32_e32 v26, v80, v82
	v_cvt_pk_bf16_f32 v26, v26, s0
	ds_write_b16 v62, v26 offset:36864
	v_mul_f32_e32 v25, 0x3fb8aa3b, v25
	v_exp_f32_e32 v25, v25
	v_mul_f32_e32 v24, 0x3fb8aa3b, v24
	v_lshlrev_b32_e32 v26, 16, v180
	v_mul_f32_e32 v26, 0x3e000000, v26
	v_mul_f32_e32 v25, v26, v25
	v_exp_f32_e32 v24, v24
	v_lshlrev_b32_e32 v83, 16, v181
	v_cvt_pk_bf16_f32 v25, v25, s0
	ds_write_b16 v62, v25 offset:27792
	v_mul_f32_e32 v25, v81, v83
	v_cvt_pk_bf16_f32 v25, v25, s0
	ds_write_b16 v62, v25 offset:37008
	v_pk_mul_f32 v[26:27], v[24:25], v[80:81] op_sel_hi:[0,1]
	v_add_f32_e32 v25, v29, v75
	v_mul_f32_e32 v28, 0xbfb8aa3b, v25
	v_mul_f32_e32 v25, 0x3fb8aa3b, v25
	v_exp_f32_e32 v25, v25
	v_exp_f32_e32 v28, v28
	v_lshlrev_b32_e32 v29, 16, v182
	v_mul_f32_e32 v29, 0x3e000000, v29
	v_mul_f32_e32 v25, v25, v29
	s_waitcnt lgkmcnt(12)
	v_lshlrev_b32_e32 v80, 16, v183
	v_cvt_pk_bf16_f32 v25, v25, s0
	ds_write_b16 v62, v25 offset:27936
	v_add_f32_e32 v25, v30, v75
	v_mul_f32_e32 v30, v28, v80
	v_cvt_pk_bf16_f32 v30, v30, s0
	ds_write_b16 v62, v30 offset:37152
	v_mul_f32_e32 v29, 0xbfb8aa3b, v25
	v_mul_f32_e32 v25, 0x3fb8aa3b, v25
	v_exp_f32_e32 v25, v25
	v_exp_f32_e32 v29, v29
	v_lshlrev_b32_e32 v30, 16, v184
	v_mul_f32_e32 v30, 0x3e000000, v30
	v_mul_f32_e32 v25, v25, v30
	v_lshlrev_b32_e32 v81, 16, v185
	v_cvt_pk_bf16_f32 v25, v25, s0
	ds_write_b16 v62, v25 offset:28080
	v_mul_f32_e32 v25, v29, v81
	v_cvt_pk_bf16_f32 v25, v25, s0
	ds_write_b16 v62, v25 offset:37296
	v_pk_mul_f32 v[28:29], v[24:25], v[28:29] op_sel_hi:[0,1]
	v_add_f32_e32 v25, v31, v75
	v_mul_f32_e32 v30, 0xbfb8aa3b, v25
	v_mul_f32_e32 v25, 0x3fb8aa3b, v25
	v_pk_mul_f32 v[28:29], v[28:29], v[80:81]
	v_exp_f32_e32 v25, v25
	v_exp_f32_e32 v30, v30
	v_lshlrev_b32_e32 v31, 16, v186
	v_mul_f32_e32 v31, 0x3e000000, v31
	v_mul_f32_e32 v25, v25, v31
	s_waitcnt lgkmcnt(12)
	v_lshlrev_b32_e32 v80, 16, v187
	v_cvt_pk_bf16_f32 v25, v25, s0
	ds_write_b16 v62, v25 offset:28224
	v_add_f32_e32 v25, v76, v75
	v_mul_f32_e32 v76, v30, v80
	v_cvt_pk_bf16_f32 v76, v76, s0
	ds_write_b16 v62, v76 offset:37440
	v_mul_f32_e32 v31, 0xbfb8aa3b, v25
	v_mul_f32_e32 v25, 0x3fb8aa3b, v25
	v_exp_f32_e32 v25, v25
	v_exp_f32_e32 v31, v31
	v_lshlrev_b32_e32 v76, 16, v188
	v_mul_f32_e32 v76, 0x3e000000, v76
	v_mul_f32_e32 v25, v25, v76
	v_lshlrev_b32_e32 v81, 16, v189
	v_cvt_pk_bf16_f32 v25, v25, s0
	ds_write_b16 v62, v25 offset:28368
	v_mul_f32_e32 v25, v31, v81
	v_cvt_pk_bf16_f32 v25, v25, s0
	ds_write_b16 v62, v25 offset:37584
	v_pk_mul_f32 v[30:31], v[24:25], v[30:31] op_sel_hi:[0,1]
	v_add_f32_e32 v25, v77, v75
	v_mul_f32_e32 v76, 0xbfb8aa3b, v25
	v_mul_f32_e32 v25, 0x3fb8aa3b, v25
	v_exp_f32_e32 v25, v25
	v_pk_mul_f32 v[30:31], v[30:31], v[80:81]
	v_lshlrev_b32_e32 v77, 16, v190
	v_mul_f32_e32 v77, 0x3e000000, v77
	v_exp_f32_e32 v76, v76
	v_mul_f32_e32 v25, v25, v77
	v_cvt_pk_bf16_f32 v25, v25, s0
	ds_write_b16 v62, v25 offset:28512
	v_add_f32_e32 v25, v78, v75
	s_waitcnt lgkmcnt(12)
	v_lshlrev_b32_e32 v80, 16, v191
	v_mul_f32_e32 v75, 0xbfb8aa3b, v25
	v_exp_f32_e32 v77, v75
	v_mul_f32_e32 v75, v76, v80
	v_cvt_pk_bf16_f32 v75, v75, s0
	ds_write_b16 v62, v75 offset:37728
	v_mul_f32_e32 v25, 0x3fb8aa3b, v25
	v_exp_f32_e32 v25, v25
	v_pk_mul_f32 v[26:27], v[26:27], v[82:83]
	v_lshlrev_b32_e32 v75, 16, v192
	v_mul_f32_e32 v75, 0x3e000000, v75
	v_mul_f32_e32 v25, v25, v75
	v_lshlrev_b32_e32 v81, 16, v193
	v_cvt_pk_bf16_f32 v25, v25, s0
	ds_write_b16 v62, v25 offset:28656
	v_mul_f32_e32 v25, v77, v81
	v_cvt_pk_bf16_f32 v25, v25, s0
	v_pk_mul_f32 v[76:77], v[24:25], v[76:77] op_sel_hi:[0,1]
	v_pk_mul_f32 v[76:77], v[76:77], v[80:81]
	ds_write_b16 v62, v25 offset:37872
	v_cvt_pk_bf16_f32 v26, v26, v27
	v_cvt_pk_bf16_f32 v27, v28, v29
	v_cvt_pk_bf16_f32 v28, v30, v31
	v_cvt_pk_bf16_f32 v29, v76, v77
	v_add_u32_e32 v25, s8, v63
	ds_write_b128 v25, v[26:29] offset:46080
	s_and_saveexec_b64 s[8:9], s[58:59]
	s_cbranch_execz .LBB0_487
	s_mul_i32 s30, s30, 0xa200
	v_add_u32_e32 v25, s30, v67
	ds_write_b32 v25, v24
	s_branch .LBB0_487
